# peeled first K-iteration of the three GEMM K-loops with SrcC=0 on first touch; accumulator zeroing (128 v_mov per wave per unit) removed
# speedup vs baseline: 1.0085x; 1.0085x over previous
.LBB0_233:
	v_mov_b64_e32 v[0:1], 0x5a0
	s_ashr_i32 s95, s94, 31
	v_cmp_lt_i64_e32 vcc, s[34:35], v[0:1]
	s_lshl_b64 s[34:35], s[94:95], 20
	s_add_u32 s96, s56, s34
	s_addc_u32 s97, s57, s35
	s_and_b64 s[34:35], vcc, exec
	s_cselect_b32 s9, s97, s11
	s_cselect_b32 s89, s96, s10
	s_ashr_i32 s71, s70, 31
	s_lshl_b64 s[34:35], s[70:71], 20
	s_add_u32 s98, s82, s34
	s_addc_u32 s99, s83, s35
	s_and_b64 s[34:35], vcc, exec
	s_cselect_b32 s71, s99, s29
	s_cselect_b32 s91, s98, s28
	s_add_u32 s10, s10, 0x80080
	s_addc_u32 s11, s11, 0
	s_add_u32 s93, s28, 0x100
	s_addc_u32 s95, s29, 0
	s_mov_b32 vcc_lo, -2
	ds_read_b128 v[136:139], v167
	ds_read_b128 v[140:143], v167 offset:1024
	ds_read_b128 v[144:147], v167 offset:2048
	ds_read_b128 v[148:151], v167 offset:3072
	s_add_u32 s3, s10, 0xfff80080
	s_addc_u32 s28, s11, -1
	s_cmp_eq_u32 vcc_lo, 28
	s_cselect_b32 s35, s9, s28
	s_cselect_b32 s34, s89, s3
	s_cselect_b32 s29, s71, s95
	s_cselect_b32 s28, s91, s93
	v_lshl_add_u64 v[152:153], s[10:11], 0, v[132:133]
	s_add_i32 m0, s62, 0xc000
	ds_read_b128 v[172:175], v168
	ds_read_b128 v[190:193], v168 offset:1024
	ds_read_b128 v[194:197], v168 offset:2048
	ds_read_b128 v[198:201], v168 offset:3072
	ds_read_b128 v[202:205], v168 offset:4096
	ds_read_b128 v[206:209], v168 offset:5120
	ds_read_b128 v[224:227], v168 offset:6144
	ds_read_b128 v[228:231], v168 offset:7168
	global_load_lds_dwordx4 v[152:153], off
	v_lshl_add_u64 v[152:153], s[10:11], 0, v[134:135]
	s_add_i32 m0, s62, 0xe000
	s_nop 0
	global_load_lds_dwordx4 v[152:153], off
	s_waitcnt lgkmcnt(8)
	s_barrier
	s_waitcnt lgkmcnt(0)
	v_mfma_f32_16x16x32_bf16 v[124:127], v[136:139], v[172:175], 0
	v_mfma_f32_16x16x32_bf16 v[116:119], v[144:147], v[172:175], 0
	v_mfma_f32_16x16x32_bf16 v[108:111], v[136:139], v[194:197], 0
	v_mfma_f32_16x16x32_bf16 v[100:103], v[144:147], v[194:197], 0
	v_mfma_f32_16x16x32_bf16 v[92:95], v[136:139], v[202:205], 0
	v_mfma_f32_16x16x32_bf16 v[84:87], v[144:147], v[202:205], 0
	v_mfma_f32_16x16x32_bf16 v[76:79], v[136:139], v[224:227], 0
	v_mfma_f32_16x16x32_bf16 v[68:71], v[144:147], v[224:227], 0
	v_mfma_f32_16x16x32_bf16 v[124:127], v[140:143], v[190:193], v[124:127]
	v_mfma_f32_16x16x32_bf16 v[116:119], v[148:151], v[190:193], v[116:119]
	v_mfma_f32_16x16x32_bf16 v[108:111], v[140:143], v[198:201], v[108:111]
	v_mfma_f32_16x16x32_bf16 v[100:103], v[148:151], v[198:201], v[100:103]
	v_mfma_f32_16x16x32_bf16 v[92:95], v[140:143], v[206:209], v[92:95]
	v_mfma_f32_16x16x32_bf16 v[84:87], v[148:151], v[206:209], v[84:87]
	v_mfma_f32_16x16x32_bf16 v[76:79], v[140:143], v[228:231], v[76:79]
	v_mfma_f32_16x16x32_bf16 v[68:71], v[148:151], v[228:231], v[68:71]
	s_barrier
	s_add_i32 s3, s84, s61
	v_lshl_add_u64 v[152:153], s[28:29], 0, v[184:185]
	s_mov_b32 m0, s3
	ds_read_b128 v[232:235], v169
	ds_read_b128 v[236:239], v169 offset:1024
	ds_read_b128 v[240:243], v169 offset:2048
	ds_read_b128 v[244:247], v169 offset:3072
	global_load_lds_dwordx4 v[152:153], off
	v_lshl_add_u64 v[248:249], s[28:29], 0, v[188:189]
	s_add_i32 m0, s3, 0x2000
	s_nop 0
	global_load_lds_dwordx4 v[248:249], off
	s_barrier
	s_waitcnt lgkmcnt(0)
	v_mfma_f32_16x16x32_bf16 v[120:123], v[232:235], v[172:175], 0
	v_mfma_f32_16x16x32_bf16 v[112:115], v[240:243], v[172:175], 0
	v_mfma_f32_16x16x32_bf16 v[104:107], v[232:235], v[194:197], 0
	v_mfma_f32_16x16x32_bf16 v[96:99], v[240:243], v[194:197], 0
	v_mfma_f32_16x16x32_bf16 v[88:91], v[232:235], v[202:205], 0
	v_mfma_f32_16x16x32_bf16 v[80:83], v[240:243], v[202:205], 0
	v_mfma_f32_16x16x32_bf16 v[72:75], v[232:235], v[224:227], 0
	v_mfma_f32_16x16x32_bf16 v[64:67], v[240:243], v[224:227], 0
	v_mfma_f32_16x16x32_bf16 v[120:123], v[236:239], v[190:193], v[120:123]
	v_mfma_f32_16x16x32_bf16 v[112:115], v[244:247], v[190:193], v[112:115]
	v_mfma_f32_16x16x32_bf16 v[104:107], v[236:239], v[198:201], v[104:107]
	v_mfma_f32_16x16x32_bf16 v[96:99], v[244:247], v[198:201], v[96:99]
	v_mfma_f32_16x16x32_bf16 v[88:91], v[236:239], v[206:209], v[88:91]
	v_mfma_f32_16x16x32_bf16 v[80:83], v[244:247], v[206:209], v[80:83]
	v_mfma_f32_16x16x32_bf16 v[72:75], v[236:239], v[228:231], v[72:75]
	v_mfma_f32_16x16x32_bf16 v[64:67], v[244:247], v[228:231], v[64:67]
	s_mov_b32 m0, s62
	v_lshl_add_u64 v[250:251], s[34:35], 0, v[182:183]
	s_barrier
	ds_read_b128 v[172:175], v168 offset:16384
	ds_read_b128 v[190:193], v168 offset:17408
	ds_read_b128 v[194:197], v168 offset:18432
	ds_read_b128 v[198:201], v168 offset:19456
	ds_read_b128 v[202:205], v168 offset:20480
	ds_read_b128 v[206:209], v168 offset:21504
	ds_read_b128 v[224:227], v168 offset:22528
	ds_read_b128 v[228:231], v168 offset:23552
	global_load_lds_dwordx4 v[250:251], off
	v_lshl_add_u64 v[252:253], s[34:35], 0, v[186:187]
	s_mov_b32 m0, s63
	s_nop 0
	global_load_lds_dwordx4 v[252:253], off
	s_barrier
	s_waitcnt lgkmcnt(0)
	v_mfma_f32_16x16x32_bf16 v[60:63], v[136:139], v[172:175], 0
	v_mfma_f32_16x16x32_bf16 v[52:55], v[144:147], v[172:175], 0
	v_mfma_f32_16x16x32_bf16 v[44:47], v[136:139], v[194:197], 0
	v_mfma_f32_16x16x32_bf16 v[36:39], v[144:147], v[194:197], 0
	v_mfma_f32_16x16x32_bf16 v[28:31], v[136:139], v[202:205], 0
	v_mfma_f32_16x16x32_bf16 v[20:23], v[144:147], v[202:205], 0
	v_mfma_f32_16x16x32_bf16 v[12:15], v[136:139], v[224:227], 0
	v_mfma_f32_16x16x32_bf16 v[4:7], v[144:147], v[224:227], 0
	v_mfma_f32_16x16x32_bf16 v[60:63], v[140:143], v[190:193], v[60:63]
	v_mfma_f32_16x16x32_bf16 v[52:55], v[148:151], v[190:193], v[52:55]
	v_mfma_f32_16x16x32_bf16 v[44:47], v[140:143], v[198:201], v[44:47]
	v_mfma_f32_16x16x32_bf16 v[36:39], v[148:151], v[198:201], v[36:39]
	v_mfma_f32_16x16x32_bf16 v[28:31], v[140:143], v[206:209], v[28:31]
	v_mfma_f32_16x16x32_bf16 v[20:23], v[148:151], v[206:209], v[20:23]
	v_mfma_f32_16x16x32_bf16 v[12:15], v[140:143], v[228:231], v[12:15]
	v_mfma_f32_16x16x32_bf16 v[4:7], v[148:151], v[228:231], v[4:7]
	s_barrier
	s_add_u32 s74, s28, 0x80000
	s_addc_u32 s75, s29, 0
	s_add_i32 s3, s85, s61
	v_lshl_add_u64 v[136:137], s[74:75], 0, v[184:185]
	s_mov_b32 m0, s3
	s_nop 0
	global_load_lds_dwordx4 v[136:137], off
	v_lshl_add_u64 v[136:137], s[74:75], 0, v[188:189]
	s_add_i32 m0, s3, 0x2000
	s_nop 0
	global_load_lds_dwordx4 v[136:137], off
	s_waitcnt vmcnt(6)
	s_barrier
	v_mfma_f32_16x16x32_bf16 v[56:59], v[232:235], v[172:175], 0
	v_mfma_f32_16x16x32_bf16 v[48:51], v[240:243], v[172:175], 0
	v_mfma_f32_16x16x32_bf16 v[40:43], v[232:235], v[194:197], 0
	v_mfma_f32_16x16x32_bf16 v[32:35], v[240:243], v[194:197], 0
	v_mfma_f32_16x16x32_bf16 v[24:27], v[232:235], v[202:205], 0
	v_mfma_f32_16x16x32_bf16 v[16:19], v[240:243], v[202:205], 0
	v_mfma_f32_16x16x32_bf16 v[8:11], v[232:235], v[224:227], 0
	v_mfma_f32_16x16x32_bf16 v[0:3], v[240:243], v[224:227], 0
	v_mfma_f32_16x16x32_bf16 v[56:59], v[236:239], v[190:193], v[56:59]
	v_mfma_f32_16x16x32_bf16 v[48:51], v[244:247], v[190:193], v[48:51]
	v_mfma_f32_16x16x32_bf16 v[40:43], v[236:239], v[198:201], v[40:43]
	v_mfma_f32_16x16x32_bf16 v[32:35], v[244:247], v[198:201], v[32:35]
	v_mfma_f32_16x16x32_bf16 v[24:27], v[236:239], v[206:209], v[24:27]
	v_mfma_f32_16x16x32_bf16 v[16:19], v[244:247], v[206:209], v[16:19]
	v_mfma_f32_16x16x32_bf16 v[8:11], v[236:239], v[228:231], v[8:11]
	v_mfma_f32_16x16x32_bf16 v[0:3], v[244:247], v[228:231], v[0:3]
	s_add_i32 s3, 0, 0x18000
	v_add_u32_e32 v130, s3, v165
	s_barrier
	ds_read_b128 v[136:139], v130
	ds_read_b128 v[140:143], v130 offset:1024
	ds_read_b128 v[144:147], v130 offset:2048
	ds_read_b128 v[148:151], v130 offset:3072
	s_add_u32 s34, s34, 0x80000
	s_addc_u32 s35, s35, 0
	s_mov_b32 m0, s64
	v_lshl_add_u64 v[232:233], s[34:35], 0, v[182:183]
	ds_read_b128 v[172:175], v168 offset:32768
	ds_read_b128 v[190:193], v168 offset:33792
	ds_read_b128 v[194:197], v168 offset:34816
	ds_read_b128 v[198:201], v168 offset:35840
	ds_read_b128 v[202:205], v168 offset:36864
	ds_read_b128 v[206:209], v168 offset:37888
	ds_read_b128 v[224:227], v168 offset:38912
	ds_read_b128 v[228:231], v168 offset:39936
	global_load_lds_dwordx4 v[232:233], off
	v_lshl_add_u64 v[232:233], s[34:35], 0, v[186:187]
	s_mov_b32 m0, s65
	s_nop 0
	global_load_lds_dwordx4 v[232:233], off
	s_waitcnt lgkmcnt(8)
	s_barrier
	s_waitcnt lgkmcnt(0)
	v_mfma_f32_16x16x32_bf16 v[124:127], v[136:139], v[172:175], v[124:127]
	v_mfma_f32_16x16x32_bf16 v[116:119], v[144:147], v[172:175], v[116:119]
	v_mfma_f32_16x16x32_bf16 v[108:111], v[136:139], v[194:197], v[108:111]
	v_mfma_f32_16x16x32_bf16 v[100:103], v[144:147], v[194:197], v[100:103]
	v_mfma_f32_16x16x32_bf16 v[92:95], v[136:139], v[202:205], v[92:95]
	v_mfma_f32_16x16x32_bf16 v[84:87], v[144:147], v[202:205], v[84:87]
	v_mfma_f32_16x16x32_bf16 v[76:79], v[136:139], v[224:227], v[76:79]
	v_mfma_f32_16x16x32_bf16 v[68:71], v[144:147], v[224:227], v[68:71]
	v_mfma_f32_16x16x32_bf16 v[124:127], v[140:143], v[190:193], v[124:127]
	v_mfma_f32_16x16x32_bf16 v[116:119], v[148:151], v[190:193], v[116:119]
	v_mfma_f32_16x16x32_bf16 v[108:111], v[140:143], v[198:201], v[108:111]
	v_mfma_f32_16x16x32_bf16 v[100:103], v[148:151], v[198:201], v[100:103]
	v_mfma_f32_16x16x32_bf16 v[92:95], v[140:143], v[206:209], v[92:95]
	v_mfma_f32_16x16x32_bf16 v[84:87], v[148:151], v[206:209], v[84:87]
	v_mfma_f32_16x16x32_bf16 v[76:79], v[140:143], v[228:231], v[76:79]
	v_mfma_f32_16x16x32_bf16 v[68:71], v[148:151], v[228:231], v[68:71]
	s_barrier
	s_add_i32 s33, 0, 0x1c000
	s_add_i32 s3, s3, s61
	v_add_u32_e32 v130, s33, v165
	v_lshl_add_u64 v[152:153], v[152:153], 0, s[86:87]
	s_mov_b32 m0, s3
	ds_read_b128 v[232:235], v130
	ds_read_b128 v[236:239], v130 offset:1024
	ds_read_b128 v[240:243], v130 offset:2048
	ds_read_b128 v[244:247], v130 offset:3072
	global_load_lds_dwordx4 v[152:153], off
	v_lshl_add_u64 v[152:153], v[248:249], 0, s[86:87]
	s_add_i32 m0, s3, 0x2000
	s_nop 0
	global_load_lds_dwordx4 v[152:153], off
	s_barrier
	s_waitcnt lgkmcnt(0)
	v_mfma_f32_16x16x32_bf16 v[120:123], v[232:235], v[172:175], v[120:123]
	v_mfma_f32_16x16x32_bf16 v[112:115], v[240:243], v[172:175], v[112:115]
	v_mfma_f32_16x16x32_bf16 v[104:107], v[232:235], v[194:197], v[104:107]
	v_mfma_f32_16x16x32_bf16 v[96:99], v[240:243], v[194:197], v[96:99]
	v_mfma_f32_16x16x32_bf16 v[88:91], v[232:235], v[202:205], v[88:91]
	v_mfma_f32_16x16x32_bf16 v[80:83], v[240:243], v[202:205], v[80:83]
	v_mfma_f32_16x16x32_bf16 v[72:75], v[232:235], v[224:227], v[72:75]
	v_mfma_f32_16x16x32_bf16 v[64:67], v[240:243], v[224:227], v[64:67]
	v_mfma_f32_16x16x32_bf16 v[120:123], v[236:239], v[190:193], v[120:123]
	v_mfma_f32_16x16x32_bf16 v[112:115], v[244:247], v[190:193], v[112:115]
	v_mfma_f32_16x16x32_bf16 v[104:107], v[236:239], v[198:201], v[104:107]
	v_mfma_f32_16x16x32_bf16 v[96:99], v[244:247], v[198:201], v[96:99]
	v_mfma_f32_16x16x32_bf16 v[88:91], v[236:239], v[206:209], v[88:91]
	v_mfma_f32_16x16x32_bf16 v[80:83], v[244:247], v[206:209], v[80:83]
	v_mfma_f32_16x16x32_bf16 v[72:75], v[236:239], v[228:231], v[72:75]
	v_mfma_f32_16x16x32_bf16 v[64:67], v[244:247], v[228:231], v[64:67]
	s_mov_b32 m0, s67
	v_lshl_add_u64 v[152:153], v[250:251], 0, s[86:87]
	s_barrier
	ds_read_b128 v[172:175], v168 offset:49152
	ds_read_b128 v[190:193], v168 offset:50176
	ds_read_b128 v[194:197], v168 offset:51200
	ds_read_b128 v[198:201], v168 offset:52224
	ds_read_b128 v[202:205], v168 offset:53248
	ds_read_b128 v[206:209], v168 offset:54272
	ds_read_b128 v[224:227], v168 offset:55296
	ds_read_b128 v[228:231], v168 offset:56320
	global_load_lds_dwordx4 v[152:153], off
	v_lshl_add_u64 v[152:153], v[252:253], 0, s[86:87]
	s_mov_b32 m0, s68
	s_nop 0
	global_load_lds_dwordx4 v[152:153], off
	s_barrier
	s_waitcnt lgkmcnt(0)
	v_mfma_f32_16x16x32_bf16 v[60:63], v[136:139], v[172:175], v[60:63]
	v_mfma_f32_16x16x32_bf16 v[52:55], v[144:147], v[172:175], v[52:55]
	v_mfma_f32_16x16x32_bf16 v[44:47], v[136:139], v[194:197], v[44:47]
	v_mfma_f32_16x16x32_bf16 v[36:39], v[144:147], v[194:197], v[36:39]
	v_mfma_f32_16x16x32_bf16 v[28:31], v[136:139], v[202:205], v[28:31]
	v_mfma_f32_16x16x32_bf16 v[20:23], v[144:147], v[202:205], v[20:23]
	v_mfma_f32_16x16x32_bf16 v[12:15], v[136:139], v[224:227], v[12:15]
	v_mfma_f32_16x16x32_bf16 v[4:7], v[144:147], v[224:227], v[4:7]
	v_mfma_f32_16x16x32_bf16 v[60:63], v[140:143], v[190:193], v[60:63]
	v_mfma_f32_16x16x32_bf16 v[52:55], v[148:151], v[190:193], v[52:55]
	v_mfma_f32_16x16x32_bf16 v[44:47], v[140:143], v[198:201], v[44:47]
	v_mfma_f32_16x16x32_bf16 v[36:39], v[148:151], v[198:201], v[36:39]
	v_mfma_f32_16x16x32_bf16 v[28:31], v[140:143], v[206:209], v[28:31]
	v_mfma_f32_16x16x32_bf16 v[20:23], v[148:151], v[206:209], v[20:23]
	v_mfma_f32_16x16x32_bf16 v[12:15], v[140:143], v[228:231], v[12:15]
	v_mfma_f32_16x16x32_bf16 v[4:7], v[148:151], v[228:231], v[4:7]
	s_barrier
	s_add_u32 s28, s28, 0x80080
	s_addc_u32 s29, s29, 0
	s_add_i32 s3, s33, s61
	v_lshl_add_u64 v[136:137], s[28:29], 0, v[184:185]
	s_mov_b32 m0, s3
	s_nop 0
	global_load_lds_dwordx4 v[136:137], off
	v_lshl_add_u64 v[136:137], s[28:29], 0, v[188:189]
	s_add_i32 m0, s3, 0x2000
	s_nop 0
	global_load_lds_dwordx4 v[136:137], off
	s_waitcnt vmcnt(6)
	s_barrier
	v_mfma_f32_16x16x32_bf16 v[56:59], v[232:235], v[172:175], v[56:59]
	v_mfma_f32_16x16x32_bf16 v[48:51], v[240:243], v[172:175], v[48:51]
	v_mfma_f32_16x16x32_bf16 v[40:43], v[232:235], v[194:197], v[40:43]
	v_mfma_f32_16x16x32_bf16 v[32:35], v[240:243], v[194:197], v[32:35]
	v_mfma_f32_16x16x32_bf16 v[24:27], v[232:235], v[202:205], v[24:27]
	v_mfma_f32_16x16x32_bf16 v[16:19], v[240:243], v[202:205], v[16:19]
	v_mfma_f32_16x16x32_bf16 v[8:11], v[232:235], v[224:227], v[8:11]
	v_mfma_f32_16x16x32_bf16 v[0:3], v[240:243], v[224:227], v[0:3]
	v_mfma_f32_16x16x32_bf16 v[56:59], v[236:239], v[190:193], v[56:59]
	v_mfma_f32_16x16x32_bf16 v[48:51], v[244:247], v[190:193], v[48:51]
	v_mfma_f32_16x16x32_bf16 v[40:43], v[236:239], v[198:201], v[40:43]
	v_mfma_f32_16x16x32_bf16 v[32:35], v[244:247], v[198:201], v[32:35]
	v_mfma_f32_16x16x32_bf16 v[24:27], v[236:239], v[206:209], v[24:27]
	v_mfma_f32_16x16x32_bf16 v[16:19], v[244:247], v[206:209], v[16:19]
	v_mfma_f32_16x16x32_bf16 v[8:11], v[236:239], v[228:231], v[8:11]
	v_mfma_f32_16x16x32_bf16 v[0:3], v[244:247], v[228:231], v[0:3]
	s_add_i32 vcc_lo, vcc_lo, 2
	s_add_u32 s10, s10, 0x100
	s_addc_u32 s11, s11, 0
	s_add_u32 s93, s93, 0x100
	s_addc_u32 s95, s95, 0
	s_cmp_gt_u32 vcc_lo, 29
	s_barrier
	s_cbranch_scc1 .Lpeel_done_in

.Lpeel_done_in:
	v_lshl_add_u32 v136, s8, 8, v129
	s_cmp_gt_i32 s92, 15
	s_mov_b64 s[8:9], -1
	s_cbranch_scc0 .LBB0_285
	s_lshr_b32 s3, s92, 3
	s_add_i32 s3, s3, -2
	s_cmp_eq_u32 s3, 0
	s_cselect_b64 s[8:9], -1, 0
	v_mov_b32_e32 v130, 0xbfb8aa3b
	v_mov_b32_e32 v137, 0xc0135761
	s_cmp_eq_u32 s3, 1
	v_cndmask_b32_e64 v138, v130, v137, s[8:9]
	s_cselect_b64 s[28:29], -1, 0
	s_cmp_lg_u32 s3, 1
	v_cndmask_b32_e64 v140, 0, v170, s[8:9]
	s_cselect_b64 s[10:11], -1, 0
	v_mov_b32_e32 v141, v140
	v_mov_b32_e32 v139, v138
	s_and_b64 vcc, exec, s[28:29]
	s_cbranch_vccnz .LBB0_238
	v_pk_mul_f32 v[142:143], v[126:127], v[126:127]
	v_pk_mul_f32 v[144:145], v[124:125], v[124:125]
	v_pk_mul_f32 v[146:147], v[118:119], v[118:119]
	v_pk_mul_f32 v[148:149], v[116:117], v[116:117]
	v_pk_fma_f32 v[144:145], v[140:141], v[144:145], v[138:139]
	v_pk_fma_f32 v[142:143], v[140:141], v[142:143], v[138:139]
	v_pk_fma_f32 v[148:149], v[140:141], v[148:149], v[138:139]
	v_pk_fma_f32 v[146:147], v[140:141], v[146:147], v[138:139]
	v_pk_mul_f32 v[144:145], v[124:125], v[144:145]
	v_pk_mul_f32 v[142:143], v[126:127], v[142:143]
	v_pk_mul_f32 v[148:149], v[116:117], v[148:149]
	v_pk_mul_f32 v[146:147], v[118:119], v[146:147]
	v_exp_f32_e32 v144, v144
	v_exp_f32_e32 v145, v145
	v_exp_f32_e32 v142, v142
	v_exp_f32_e32 v143, v143
	v_exp_f32_e32 v148, v148
	v_exp_f32_e32 v149, v149
	v_exp_f32_e32 v146, v146
	v_exp_f32_e32 v147, v147
	v_pk_add_f32 v[144:145], v[144:145], 1.0 op_sel_hi:[1,0]
	v_pk_add_f32 v[142:143], v[142:143], 1.0 op_sel_hi:[1,0]
	v_pk_add_f32 v[148:149], v[148:149], 1.0 op_sel_hi:[1,0]
	v_pk_add_f32 v[146:147], v[146:147], 1.0 op_sel_hi:[1,0]
	v_rcp_f32_e32 v144, v144
	v_rcp_f32_e32 v145, v145
	v_rcp_f32_e32 v142, v142
	v_rcp_f32_e32 v143, v143
	v_rcp_f32_e32 v152, v148
	v_rcp_f32_e32 v153, v149
	v_rcp_f32_e32 v150, v146
	v_rcp_f32_e32 v151, v147
	v_pk_mul_f32 v[146:147], v[126:127], v[142:143]
	v_pk_mul_f32 v[148:149], v[124:125], v[144:145]
	v_pk_mul_f32 v[152:153], v[116:117], v[152:153]
	v_pk_mul_f32 v[150:151], v[118:119], v[150:151]
	s_branch .LBB0_239

.LBB0_557:
	s_ashr_i32 s41, s40, 31
	s_xor_b64 s[44:45], s[34:35], -1
	s_lshl_b64 s[46:47], s[40:41], 20
	s_add_u32 s3, s8, s46
	s_addc_u32 s39, s9, s47
	s_ashr_i32 s43, s42, 31
	s_lshl_b64 s[48:49], s[42:43], 1
	s_add_u32 s46, s3, s48
	s_addc_u32 s47, s39, s49
	s_and_b64 s[50:51], s[34:35], exec
	s_cselect_b32 s41, s47, s11
	s_cselect_b32 s43, s46, s10
	s_ashr_i32 s39, s38, 31
	s_lshl_b64 s[50:51], s[38:39], 20
	s_add_u32 s3, s72, s50
	s_addc_u32 s39, s73, s51
	s_add_u32 s48, s3, s48
	s_addc_u32 s49, s39, s49
	s_and_b64 s[34:35], s[34:35], exec
	s_cselect_b32 s39, s49, s29
	s_cselect_b32 s50, s48, s28
	s_add_u32 s10, s10, 0x80080
	s_addc_u32 s11, s11, 0
	s_add_u32 s51, s28, 0x100
	s_addc_u32 s85, s29, 0
	s_mov_b32 s86, 2
	ds_read_b128 v[40:43], v228
	ds_read_b128 v[44:47], v228 offset:1024
	ds_read_b128 v[52:55], v228 offset:2048
	ds_read_b128 v[60:63], v228 offset:3072
	s_add_u32 s3, s10, 0xfff80080
	s_addc_u32 s28, s11, -1
	s_cmp_eq_u32 s84, s86
	s_cselect_b32 s35, s41, s28
	s_cselect_b32 s34, s43, s3
	s_cselect_b32 s29, s39, s85
	s_cselect_b32 s28, s50, s51
	v_lshl_add_u64 v[198:199], s[10:11], 0, v[192:193]
	s_add_i32 m0, s61, 0xc000
	ds_read_b128 v[144:147], v229
	ds_read_b128 v[148:151], v229 offset:1024
	ds_read_b128 v[152:155], v229 offset:2048
	ds_read_b128 v[156:159], v229 offset:3072
	ds_read_b128 v[160:163], v229 offset:4096
	ds_read_b128 v[164:167], v229 offset:5120
	ds_read_b128 v[168:171], v229 offset:6144
	ds_read_b128 v[172:175], v229 offset:7168
	global_load_lds_dwordx4 v[198:199], off
	v_lshl_add_u64 v[198:199], s[10:11], 0, v[194:195]
	s_add_i32 m0, s61, 0xe000
	s_nop 0
	global_load_lds_dwordx4 v[198:199], off
	s_waitcnt lgkmcnt(8)
	s_barrier
	s_waitcnt lgkmcnt(0)
	v_mfma_f32_16x16x32_bf16 v[140:143], v[40:43], v[144:147], 0
	v_mfma_f32_16x16x32_bf16 v[136:139], v[52:55], v[144:147], 0
	v_mfma_f32_16x16x32_bf16 v[124:127], v[40:43], v[152:155], 0
	v_mfma_f32_16x16x32_bf16 v[120:123], v[52:55], v[152:155], 0
	v_mfma_f32_16x16x32_bf16 v[108:111], v[40:43], v[160:163], 0
	v_mfma_f32_16x16x32_bf16 v[104:107], v[52:55], v[160:163], 0
	v_mfma_f32_16x16x32_bf16 v[92:95], v[40:43], v[168:171], 0
	v_mfma_f32_16x16x32_bf16 v[88:91], v[52:55], v[168:171], 0
	v_mfma_f32_16x16x32_bf16 v[140:143], v[44:47], v[148:151], v[140:143]
	v_mfma_f32_16x16x32_bf16 v[136:139], v[60:63], v[148:151], v[136:139]
	v_mfma_f32_16x16x32_bf16 v[124:127], v[44:47], v[156:159], v[124:127]
	v_mfma_f32_16x16x32_bf16 v[120:123], v[60:63], v[156:159], v[120:123]
	v_mfma_f32_16x16x32_bf16 v[108:111], v[44:47], v[164:167], v[108:111]
	v_mfma_f32_16x16x32_bf16 v[104:107], v[60:63], v[164:167], v[104:107]
	v_mfma_f32_16x16x32_bf16 v[92:95], v[44:47], v[172:175], v[92:95]
	v_mfma_f32_16x16x32_bf16 v[88:91], v[60:63], v[172:175], v[88:91]
	s_barrier
	s_add_i32 s3, s79, s69
	v_lshl_add_u64 v[236:237], s[28:29], 0, v[184:185]
	s_mov_b32 m0, s3
	ds_read_b128 v[198:201], v230
	ds_read_b128 v[202:205], v230 offset:1024
	ds_read_b128 v[206:209], v230 offset:2048
	ds_read_b128 v[232:235], v230 offset:3072
	global_load_lds_dwordx4 v[236:237], off
	v_lshl_add_u64 v[238:239], s[28:29], 0, v[188:189]
	s_add_i32 m0, s3, 0x2000
	s_nop 0
	global_load_lds_dwordx4 v[238:239], off
	s_barrier
	s_waitcnt lgkmcnt(0)
	v_mfma_f32_16x16x32_bf16 v[132:135], v[198:201], v[144:147], 0
	v_mfma_f32_16x16x32_bf16 v[128:131], v[206:209], v[144:147], 0
	v_mfma_f32_16x16x32_bf16 v[116:119], v[198:201], v[152:155], 0
	v_mfma_f32_16x16x32_bf16 v[112:115], v[206:209], v[152:155], 0
	v_mfma_f32_16x16x32_bf16 v[100:103], v[198:201], v[160:163], 0
	v_mfma_f32_16x16x32_bf16 v[96:99], v[206:209], v[160:163], 0
	v_mfma_f32_16x16x32_bf16 v[84:87], v[198:201], v[168:171], 0
	v_mfma_f32_16x16x32_bf16 v[80:83], v[206:209], v[168:171], 0
	v_mfma_f32_16x16x32_bf16 v[132:135], v[202:205], v[148:151], v[132:135]
	v_mfma_f32_16x16x32_bf16 v[128:131], v[232:235], v[148:151], v[128:131]
	v_mfma_f32_16x16x32_bf16 v[116:119], v[202:205], v[156:159], v[116:119]
	v_mfma_f32_16x16x32_bf16 v[112:115], v[232:235], v[156:159], v[112:115]
	v_mfma_f32_16x16x32_bf16 v[100:103], v[202:205], v[164:167], v[100:103]
	v_mfma_f32_16x16x32_bf16 v[96:99], v[232:235], v[164:167], v[96:99]
	v_mfma_f32_16x16x32_bf16 v[84:87], v[202:205], v[172:175], v[84:87]
	v_mfma_f32_16x16x32_bf16 v[80:83], v[232:235], v[172:175], v[80:83]
	s_mov_b32 m0, s61
	v_lshl_add_u64 v[240:241], s[34:35], 0, v[182:183]
	s_barrier
	ds_read_b128 v[144:147], v229 offset:16384
	ds_read_b128 v[148:151], v229 offset:17408
	ds_read_b128 v[152:155], v229 offset:18432
	ds_read_b128 v[156:159], v229 offset:19456
	ds_read_b128 v[160:163], v229 offset:20480
	ds_read_b128 v[164:167], v229 offset:21504
	ds_read_b128 v[168:171], v229 offset:22528
	ds_read_b128 v[172:175], v229 offset:23552
	global_load_lds_dwordx4 v[240:241], off
	v_lshl_add_u64 v[242:243], s[34:35], 0, v[186:187]
	s_mov_b32 m0, s63
	s_nop 0
	global_load_lds_dwordx4 v[242:243], off
	s_barrier
	s_waitcnt lgkmcnt(0)
	v_mfma_f32_16x16x32_bf16 v[76:79], v[40:43], v[144:147], 0
	v_mfma_f32_16x16x32_bf16 v[72:75], v[52:55], v[144:147], 0
	v_mfma_f32_16x16x32_bf16 v[56:59], v[40:43], v[152:155], 0
	v_mfma_f32_16x16x32_bf16 v[48:51], v[52:55], v[152:155], 0
	v_mfma_f32_16x16x32_bf16 v[28:31], v[40:43], v[160:163], 0
	v_mfma_f32_16x16x32_bf16 v[24:27], v[52:55], v[160:163], 0
	v_mfma_f32_16x16x32_bf16 v[12:15], v[40:43], v[168:171], 0
	v_mfma_f32_16x16x32_bf16 v[8:11], v[52:55], v[168:171], 0
	v_mfma_f32_16x16x32_bf16 v[76:79], v[44:47], v[148:151], v[76:79]
	v_mfma_f32_16x16x32_bf16 v[72:75], v[60:63], v[148:151], v[72:75]
	v_mfma_f32_16x16x32_bf16 v[56:59], v[44:47], v[156:159], v[56:59]
	v_mfma_f32_16x16x32_bf16 v[48:51], v[60:63], v[156:159], v[48:51]
	v_mfma_f32_16x16x32_bf16 v[28:31], v[44:47], v[164:167], v[28:31]
	v_mfma_f32_16x16x32_bf16 v[24:27], v[60:63], v[164:167], v[24:27]
	v_mfma_f32_16x16x32_bf16 v[12:15], v[44:47], v[172:175], v[12:15]
	v_mfma_f32_16x16x32_bf16 v[8:11], v[60:63], v[172:175], v[8:11]
	s_barrier
	s_add_u32 s88, s28, 0x80000
	s_addc_u32 s89, s29, 0
	s_add_i32 s3, s80, s69
	v_lshl_add_u64 v[40:41], s[88:89], 0, v[184:185]
	s_mov_b32 m0, s3
	s_nop 0
	global_load_lds_dwordx4 v[40:41], off
	v_lshl_add_u64 v[40:41], s[88:89], 0, v[188:189]
	s_add_i32 m0, s3, 0x2000
	s_nop 0
	global_load_lds_dwordx4 v[40:41], off
	s_waitcnt vmcnt(6)
	s_barrier
	v_mfma_f32_16x16x32_bf16 v[36:39], v[198:201], v[152:155], 0
	v_mfma_f32_16x16x32_bf16 v[32:35], v[206:209], v[152:155], 0
	v_mfma_f32_16x16x32_bf16 v[20:23], v[198:201], v[160:163], 0
	v_mfma_f32_16x16x32_bf16 v[16:19], v[206:209], v[160:163], 0
	v_mfma_f32_16x16x32_bf16 v[4:7], v[198:201], v[168:171], 0
	v_mfma_f32_16x16x32_bf16 v[0:3], v[206:209], v[168:171], 0
	v_mfma_f32_16x16x32_bf16 v[40:43], v[198:201], v[144:147], 0
	v_mfma_f32_16x16x32_bf16 v[44:47], v[206:209], v[144:147], 0
	v_mfma_f32_16x16x32_bf16 v[36:39], v[202:205], v[156:159], v[36:39]
	v_mfma_f32_16x16x32_bf16 v[32:35], v[232:235], v[156:159], v[32:35]
	v_mfma_f32_16x16x32_bf16 v[20:23], v[202:205], v[164:167], v[20:23]
	v_mfma_f32_16x16x32_bf16 v[16:19], v[232:235], v[164:167], v[16:19]
	v_mfma_f32_16x16x32_bf16 v[4:7], v[202:205], v[172:175], v[4:7]
	v_mfma_f32_16x16x32_bf16 v[0:3], v[232:235], v[172:175], v[0:3]
	v_mfma_f32_16x16x32_bf16 v[40:43], v[202:205], v[148:151], v[40:43]
	v_mfma_f32_16x16x32_bf16 v[44:47], v[232:235], v[148:151], v[44:47]
	s_add_i32 s3, 0, 0x18000
	v_add_u32_e32 v68, s3, v226
	s_barrier
	ds_read_b128 v[52:55], v68
	ds_read_b128 v[60:63], v68 offset:1024
	ds_read_b128 v[64:67], v68 offset:2048
	ds_read_b128 v[68:71], v68 offset:3072
	s_add_u32 s34, s34, 0x80000
	s_addc_u32 s35, s35, 0
	s_mov_b32 m0, s67
	v_lshl_add_u64 v[198:199], s[34:35], 0, v[182:183]
	ds_read_b128 v[144:147], v229 offset:32768
	ds_read_b128 v[148:151], v229 offset:33792
	ds_read_b128 v[152:155], v229 offset:34816
	ds_read_b128 v[156:159], v229 offset:35840
	ds_read_b128 v[160:163], v229 offset:36864
	ds_read_b128 v[164:167], v229 offset:37888
	ds_read_b128 v[168:171], v229 offset:38912
	ds_read_b128 v[172:175], v229 offset:39936
	global_load_lds_dwordx4 v[198:199], off
	v_lshl_add_u64 v[198:199], s[34:35], 0, v[186:187]
	s_mov_b32 m0, s70
	s_nop 0
	global_load_lds_dwordx4 v[198:199], off
	s_waitcnt lgkmcnt(8)
	s_barrier
	s_waitcnt lgkmcnt(0)
	v_mfma_f32_16x16x32_bf16 v[140:143], v[52:55], v[144:147], v[140:143]
	v_mfma_f32_16x16x32_bf16 v[136:139], v[64:67], v[144:147], v[136:139]
	v_mfma_f32_16x16x32_bf16 v[124:127], v[52:55], v[152:155], v[124:127]
	v_mfma_f32_16x16x32_bf16 v[120:123], v[64:67], v[152:155], v[120:123]
	v_mfma_f32_16x16x32_bf16 v[108:111], v[52:55], v[160:163], v[108:111]
	v_mfma_f32_16x16x32_bf16 v[104:107], v[64:67], v[160:163], v[104:107]
	v_mfma_f32_16x16x32_bf16 v[92:95], v[52:55], v[168:171], v[92:95]
	v_mfma_f32_16x16x32_bf16 v[88:91], v[64:67], v[168:171], v[88:91]
	v_mfma_f32_16x16x32_bf16 v[140:143], v[60:63], v[148:151], v[140:143]
	v_mfma_f32_16x16x32_bf16 v[136:139], v[68:71], v[148:151], v[136:139]
	v_mfma_f32_16x16x32_bf16 v[124:127], v[60:63], v[156:159], v[124:127]
	v_mfma_f32_16x16x32_bf16 v[120:123], v[68:71], v[156:159], v[120:123]
	v_mfma_f32_16x16x32_bf16 v[108:111], v[60:63], v[164:167], v[108:111]
	v_mfma_f32_16x16x32_bf16 v[104:107], v[68:71], v[164:167], v[104:107]
	v_mfma_f32_16x16x32_bf16 v[92:95], v[60:63], v[172:175], v[92:95]
	v_mfma_f32_16x16x32_bf16 v[88:91], v[68:71], v[172:175], v[88:91]
	s_barrier
	s_add_i32 s34, 0, 0x1c000
	s_add_i32 s3, s3, s69
	v_add_u32_e32 v231, s34, v226
	v_lshl_add_u64 v[236:237], v[236:237], 0, s[22:23]
	s_mov_b32 m0, s3
	ds_read_b128 v[198:201], v231
	ds_read_b128 v[202:205], v231 offset:1024
	ds_read_b128 v[206:209], v231 offset:2048
	ds_read_b128 v[232:235], v231 offset:3072
	global_load_lds_dwordx4 v[236:237], off
	v_lshl_add_u64 v[236:237], v[238:239], 0, s[22:23]
	s_add_i32 m0, s3, 0x2000
	s_nop 0
	global_load_lds_dwordx4 v[236:237], off
	s_barrier
	s_waitcnt lgkmcnt(0)
	v_mfma_f32_16x16x32_bf16 v[132:135], v[198:201], v[144:147], v[132:135]
	v_mfma_f32_16x16x32_bf16 v[128:131], v[206:209], v[144:147], v[128:131]
	v_mfma_f32_16x16x32_bf16 v[116:119], v[198:201], v[152:155], v[116:119]
	v_mfma_f32_16x16x32_bf16 v[112:115], v[206:209], v[152:155], v[112:115]
	v_mfma_f32_16x16x32_bf16 v[100:103], v[198:201], v[160:163], v[100:103]
	v_mfma_f32_16x16x32_bf16 v[96:99], v[206:209], v[160:163], v[96:99]
	v_mfma_f32_16x16x32_bf16 v[84:87], v[198:201], v[168:171], v[84:87]
	v_mfma_f32_16x16x32_bf16 v[80:83], v[206:209], v[168:171], v[80:83]
	v_mfma_f32_16x16x32_bf16 v[132:135], v[202:205], v[148:151], v[132:135]
	v_mfma_f32_16x16x32_bf16 v[128:131], v[232:235], v[148:151], v[128:131]
	v_mfma_f32_16x16x32_bf16 v[116:119], v[202:205], v[156:159], v[116:119]
	v_mfma_f32_16x16x32_bf16 v[112:115], v[232:235], v[156:159], v[112:115]
	v_mfma_f32_16x16x32_bf16 v[100:103], v[202:205], v[164:167], v[100:103]
	v_mfma_f32_16x16x32_bf16 v[96:99], v[232:235], v[164:167], v[96:99]
	v_mfma_f32_16x16x32_bf16 v[84:87], v[202:205], v[172:175], v[84:87]
	v_mfma_f32_16x16x32_bf16 v[80:83], v[232:235], v[172:175], v[80:83]
	s_mov_b32 m0, s71
	v_lshl_add_u64 v[236:237], v[240:241], 0, s[22:23]
	s_barrier
	ds_read_b128 v[144:147], v229 offset:49152
	ds_read_b128 v[148:151], v229 offset:50176
	ds_read_b128 v[152:155], v229 offset:51200
	ds_read_b128 v[156:159], v229 offset:52224
	ds_read_b128 v[160:163], v229 offset:53248
	ds_read_b128 v[164:167], v229 offset:54272
	ds_read_b128 v[168:171], v229 offset:55296
	ds_read_b128 v[172:175], v229 offset:56320
	global_load_lds_dwordx4 v[236:237], off
	v_lshl_add_u64 v[236:237], v[242:243], 0, s[22:23]
	s_mov_b32 m0, s74
	s_nop 0
	global_load_lds_dwordx4 v[236:237], off
	s_barrier
	s_waitcnt lgkmcnt(0)
	v_mfma_f32_16x16x32_bf16 v[76:79], v[52:55], v[144:147], v[76:79]
	v_mfma_f32_16x16x32_bf16 v[72:75], v[64:67], v[144:147], v[72:75]
	v_mfma_f32_16x16x32_bf16 v[56:59], v[52:55], v[152:155], v[56:59]
	v_mfma_f32_16x16x32_bf16 v[48:51], v[64:67], v[152:155], v[48:51]
	v_mfma_f32_16x16x32_bf16 v[28:31], v[52:55], v[160:163], v[28:31]
	v_mfma_f32_16x16x32_bf16 v[24:27], v[64:67], v[160:163], v[24:27]
	v_mfma_f32_16x16x32_bf16 v[12:15], v[52:55], v[168:171], v[12:15]
	v_mfma_f32_16x16x32_bf16 v[8:11], v[64:67], v[168:171], v[8:11]
	v_mfma_f32_16x16x32_bf16 v[76:79], v[60:63], v[148:151], v[76:79]
	v_mfma_f32_16x16x32_bf16 v[72:75], v[68:71], v[148:151], v[72:75]
	v_mfma_f32_16x16x32_bf16 v[56:59], v[60:63], v[156:159], v[56:59]
	v_mfma_f32_16x16x32_bf16 v[48:51], v[68:71], v[156:159], v[48:51]
	v_mfma_f32_16x16x32_bf16 v[28:31], v[60:63], v[164:167], v[28:31]
	v_mfma_f32_16x16x32_bf16 v[24:27], v[68:71], v[164:167], v[24:27]
	v_mfma_f32_16x16x32_bf16 v[12:15], v[60:63], v[172:175], v[12:15]
	v_mfma_f32_16x16x32_bf16 v[8:11], v[68:71], v[172:175], v[8:11]
	s_barrier
	s_add_u32 s28, s28, 0x80080
	s_addc_u32 s29, s29, 0
	s_add_i32 s3, s34, s69
	v_lshl_add_u64 v[52:53], s[28:29], 0, v[184:185]
	s_mov_b32 m0, s3
	s_nop 0
	global_load_lds_dwordx4 v[52:53], off
	v_lshl_add_u64 v[52:53], s[28:29], 0, v[188:189]
	s_add_i32 m0, s3, 0x2000
	s_nop 0
	global_load_lds_dwordx4 v[52:53], off
	s_waitcnt vmcnt(6)
	s_barrier
	v_mfma_f32_16x16x32_bf16 v[40:43], v[198:201], v[144:147], v[40:43]
	v_mfma_f32_16x16x32_bf16 v[68:71], v[202:205], v[148:151], v[40:43]
	v_mfma_f32_16x16x32_bf16 v[40:43], v[206:209], v[144:147], v[44:47]
	v_mfma_f32_16x16x32_bf16 v[36:39], v[198:201], v[152:155], v[36:39]
	v_mfma_f32_16x16x32_bf16 v[32:35], v[206:209], v[152:155], v[32:35]
	v_mfma_f32_16x16x32_bf16 v[20:23], v[198:201], v[160:163], v[20:23]
	v_mfma_f32_16x16x32_bf16 v[16:19], v[206:209], v[160:163], v[16:19]
	v_mfma_f32_16x16x32_bf16 v[4:7], v[198:201], v[168:171], v[4:7]
	v_mfma_f32_16x16x32_bf16 v[0:3], v[206:209], v[168:171], v[0:3]
	v_mfma_f32_16x16x32_bf16 v[64:67], v[232:235], v[148:151], v[40:43]
	v_mfma_f32_16x16x32_bf16 v[36:39], v[202:205], v[156:159], v[36:39]
	v_mfma_f32_16x16x32_bf16 v[32:35], v[232:235], v[156:159], v[32:35]
	v_mfma_f32_16x16x32_bf16 v[20:23], v[202:205], v[164:167], v[20:23]
	v_mfma_f32_16x16x32_bf16 v[16:19], v[232:235], v[164:167], v[16:19]
	v_mfma_f32_16x16x32_bf16 v[4:7], v[202:205], v[172:175], v[4:7]
	v_mfma_f32_16x16x32_bf16 v[0:3], v[232:235], v[172:175], v[0:3]
	s_add_i32 s3, s86, 2
	s_add_u32 s10, s10, 0x100
	s_addc_u32 s11, s11, 0
	s_add_u32 s51, s51, 0x100
	s_addc_u32 s85, s85, 0
	s_cmp_ge_u32 s86, s84
	s_mov_b32 s86, s3
	s_barrier
	s_cbranch_scc1 .Lpeel_done_glu

.Lpeel_done_glu:
	s_cmp_eq_u32 s84, 32
	s_cselect_b64 s[50:51], -1, 0
	s_mov_b64 s[10:11], -1
	s_and_b64 vcc, exec, s[50:51]
	s_cbranch_vccnz .LBB0_562
	s_lshl_b32 s3, s84, 6
	s_sext_i32_i16 s3, s3
	v_cvt_f32_i32_e32 v40, s3
	v_cvt_f32_i32_e32 v41, s66
	s_xor_b32 s3, s66, s3
	s_ashr_i32 s3, s3, 30
	v_rcp_iflag_f32_e32 v43, v40
	s_or_b32 s3, s3, 1
	v_cvt_pk_bf16_f32 v42, v140, v141
	v_cvt_pk_bf16_f32 v44, v136, v137
	v_mul_f32_e32 v43, v41, v43
	v_trunc_f32_e32 v43, v43
	v_fma_f32 v41, -v43, v40, v41
	v_cvt_i32_f32_e32 v43, v43
	v_cmp_ge_f32_e64 s[10:11], |v41|, |v40|
	s_and_b64 s[10:11], s[10:11], exec
	s_cselect_b32 s3, s3, 0
	v_add_u32_e32 v40, s3, v43
	v_bfe_i32 v40, v40, 0, 16
	v_ashrrev_i32_e32 v41, 31, v40
	v_lshlrev_b64 v[40:41], 22, v[40:41]
	v_lshl_add_u64 v[40:41], v[190:191], 0, v[40:41]
	v_cvt_pk_bf16_f32 v43, v142, v143
	v_cvt_pk_bf16_f32 v45, v138, v139
	s_mov_b64 s[10:11], 0x400
	global_store_dwordx4 v[40:41], v[42:45], off sc1
	s_nop 2
	v_cvt_pk_bf16_f32 v42, v132, v133
	v_cvt_pk_bf16_f32 v43, v134, v135
	v_cvt_pk_bf16_f32 v44, v128, v129
	v_cvt_pk_bf16_f32 v45, v130, v131
	v_lshl_add_u64 v[46:47], v[40:41], 0, s[10:11]
	global_store_dwordx4 v[46:47], v[42:45], off sc1
	s_nop 2
	s_mov_b64 s[10:11], 0x800
	v_cvt_pk_bf16_f32 v42, v124, v125
	v_cvt_pk_bf16_f32 v43, v126, v127
	v_cvt_pk_bf16_f32 v44, v120, v121
	v_cvt_pk_bf16_f32 v45, v122, v123
	v_lshl_add_u64 v[46:47], v[40:41], 0, s[10:11]
	global_store_dwordx4 v[46:47], v[42:45], off sc1
	s_nop 2
	s_mov_b64 s[10:11], 0xc00
	v_cvt_pk_bf16_f32 v42, v116, v117
	v_cvt_pk_bf16_f32 v43, v118, v119
	v_cvt_pk_bf16_f32 v44, v112, v113
	v_cvt_pk_bf16_f32 v45, v114, v115
	v_lshl_add_u64 v[46:47], v[40:41], 0, s[10:11]
	global_store_dwordx4 v[46:47], v[42:45], off sc1
	s_nop 2
	s_mov_b64 s[10:11], 0x1000
	v_cvt_pk_bf16_f32 v42, v108, v109
	v_cvt_pk_bf16_f32 v43, v110, v111
	v_cvt_pk_bf16_f32 v44, v104, v105
	v_cvt_pk_bf16_f32 v45, v106, v107
	v_lshl_add_u64 v[46:47], v[40:41], 0, s[10:11]
	global_store_dwordx4 v[46:47], v[42:45], off sc1
	s_nop 2
	s_mov_b64 s[10:11], 0x1400
	v_cvt_pk_bf16_f32 v42, v100, v101
	v_cvt_pk_bf16_f32 v43, v102, v103
	v_cvt_pk_bf16_f32 v44, v96, v97
	v_cvt_pk_bf16_f32 v45, v98, v99
	v_lshl_add_u64 v[46:47], v[40:41], 0, s[10:11]
	global_store_dwordx4 v[46:47], v[42:45], off sc1
	s_nop 2
	s_mov_b64 s[10:11], 0x1800
	v_cvt_pk_bf16_f32 v42, v92, v93
	v_cvt_pk_bf16_f32 v43, v94, v95
	v_cvt_pk_bf16_f32 v44, v88, v89
	v_cvt_pk_bf16_f32 v45, v90, v91
	v_lshl_add_u64 v[46:47], v[40:41], 0, s[10:11]
	global_store_dwordx4 v[46:47], v[42:45], off sc1
	s_nop 2
	s_mov_b64 s[10:11], 0x1c00
	v_cvt_pk_bf16_f32 v42, v84, v85
	v_cvt_pk_bf16_f32 v43, v86, v87
	v_cvt_pk_bf16_f32 v44, v80, v81
	v_cvt_pk_bf16_f32 v45, v82, v83
	v_lshl_add_u64 v[46:47], v[40:41], 0, s[10:11]
	global_store_dwordx4 v[46:47], v[42:45], off sc1
	s_nop 2
	s_mov_b64 s[10:11], 0x2000
	v_cvt_pk_bf16_f32 v42, v76, v77
	v_cvt_pk_bf16_f32 v43, v78, v79
	v_cvt_pk_bf16_f32 v44, v72, v73
	v_cvt_pk_bf16_f32 v45, v74, v75
	v_lshl_add_u64 v[46:47], v[40:41], 0, s[10:11]
	global_store_dwordx4 v[46:47], v[42:45], off sc1
	s_nop 2
	s_mov_b64 s[10:11], 0x2400
	v_cvt_pk_bf16_f32 v42, v68, v69
	v_cvt_pk_bf16_f32 v43, v70, v71
	v_cvt_pk_bf16_f32 v44, v64, v65
	v_cvt_pk_bf16_f32 v45, v66, v67
	v_lshl_add_u64 v[46:47], v[40:41], 0, s[10:11]
	global_store_dwordx4 v[46:47], v[42:45], off sc1
	s_nop 2
	s_mov_b64 s[10:11], 0x2800
	v_cvt_pk_bf16_f32 v42, v56, v57
	v_cvt_pk_bf16_f32 v43, v58, v59
	v_cvt_pk_bf16_f32 v44, v48, v49
	v_cvt_pk_bf16_f32 v45, v50, v51
	v_lshl_add_u64 v[46:47], v[40:41], 0, s[10:11]
	global_store_dwordx4 v[46:47], v[42:45], off sc1
	s_nop 2
	s_mov_b64 s[10:11], 0x2c00
	v_cvt_pk_bf16_f32 v42, v36, v37
	v_cvt_pk_bf16_f32 v43, v38, v39
	v_cvt_pk_bf16_f32 v44, v32, v33
	v_cvt_pk_bf16_f32 v45, v34, v35
	v_lshl_add_u64 v[46:47], v[40:41], 0, s[10:11]
	global_store_dwordx4 v[46:47], v[42:45], off sc1
	s_nop 2
	s_mov_b64 s[10:11], 0x3000
	v_cvt_pk_bf16_f32 v42, v28, v29
	v_cvt_pk_bf16_f32 v43, v30, v31
	v_cvt_pk_bf16_f32 v44, v24, v25
	v_cvt_pk_bf16_f32 v45, v26, v27
	v_lshl_add_u64 v[46:47], v[40:41], 0, s[10:11]
	global_store_dwordx4 v[46:47], v[42:45], off sc1
	s_nop 2
	s_mov_b64 s[10:11], 0x3400
	v_cvt_pk_bf16_f32 v42, v20, v21
	v_cvt_pk_bf16_f32 v43, v22, v23
	v_cvt_pk_bf16_f32 v44, v16, v17
	v_cvt_pk_bf16_f32 v45, v18, v19
	v_lshl_add_u64 v[46:47], v[40:41], 0, s[10:11]
	global_store_dwordx4 v[46:47], v[42:45], off sc1
	s_nop 2
	s_mov_b64 s[10:11], 0x3800
	v_cvt_pk_bf16_f32 v42, v12, v13
	v_cvt_pk_bf16_f32 v43, v14, v15
	v_cvt_pk_bf16_f32 v44, v8, v9
	v_cvt_pk_bf16_f32 v45, v10, v11
	v_lshl_add_u64 v[46:47], v[40:41], 0, s[10:11]
	global_store_dwordx4 v[46:47], v[42:45], off sc1
	s_nop 2
	v_cvt_pk_bf16_f32 v42, v4, v5
	v_cvt_pk_bf16_f32 v43, v6, v7
	v_cvt_pk_bf16_f32 v44, v0, v1
	v_cvt_pk_bf16_f32 v45, v2, v3
	v_lshl_add_u64 v[40:41], v[40:41], 0, s[26:27]
	global_store_dwordx4 v[40:41], v[42:45], off sc1
	s_nop 2
	s_cbranch_execz .LBB0_563

.LBB0_637:
	s_mov_b64 s[16:17], 0x80
	s_and_b32 s5, s11, 3
	s_add_i32 m0, s44, 0x18000
	v_lshl_add_u64 v[6:7], v[6:7], 0, s[16:17]
	s_lshl_b32 s40, s10, 6
	s_lshl_b32 s18, s10, 13
	s_lshl_b32 s19, s5, 12
	s_lshl_b32 s65, s5, 5
	s_lshl_b32 s66, s6, 9
	s_waitcnt vmcnt(4)
	s_barrier
	global_load_lds_dwordx4 v[6:7], off
	v_lshl_add_u64 v[4:5], v[4:5], 0, s[16:17]
	s_add_i32 m0, s44, 0x1a000
	s_add_i32 s67, s44, 0x8000
	s_add_i32 s68, s44, 0xa000
	global_load_lds_dwordx4 v[4:5], off
	v_lshl_add_u64 v[2:3], v[2:3], 0, s[16:17]
	s_mov_b32 m0, s67
	s_add_u32 s10, s8, 0x100080
	global_load_lds_dwordx4 v[2:3], off
	v_lshl_add_u64 v[0:1], v[0:1], 0, s[16:17]
	s_mov_b32 m0, s68
	s_addc_u32 s11, s9, 0
	global_load_lds_dwordx4 v[0:1], off
	s_add_i32 m0, s44, 0x1c000
	v_lshl_add_u64 v[0:1], s[10:11], 0, v[134:135]
	global_load_lds_dwordx4 v[0:1], off
	v_lshl_add_u64 v[0:1], s[10:11], 0, v[136:137]
	s_add_i32 m0, s44, 0x1e000
	v_lshrrev_b32_e32 v148, 7, v180
	global_load_lds_dwordx4 v[0:1], off
	v_lshlrev_b32_e32 v1, 2, v210
	v_lshl_or_b32 v0, v210, 6, v224
	v_and_b32_e32 v1, 32, v1
	v_bitop3_b32 v0, v0, s18, v1 bitop3:0xde
	v_or_b32_e32 v1, v218, v224
	v_bitop3_b32 v139, s19, v1, v219 bitop3:0xf6
	v_lshlrev_b32_e32 v1, 17, v148
	v_lshlrev_b32_e32 v2, 13, v216
	v_or3_b32 v1, v214, v1, v2
	v_add_u32_e32 v56, v1, v215
	v_lshlrev_b32_e32 v1, 6, v217
	v_and_b32_e32 v1, 0xfffe0000, v1
	s_mov_b64 s[10:11], 0x100080
	v_or3_b32 v1, v214, v1, v2
	v_lshl_add_u64 v[142:143], v[56:57], 0, s[10:11]
	v_add_u32_e32 v56, v1, v215
	v_or_b32_e32 v132, s40, v210
	s_waitcnt vmcnt(6)
	v_mov_b32_e32 v133, v57
	v_lshl_add_u64 v[144:145], v[56:57], 0, s[10:11]
	v_mov_b32_e32 v56, v57
	v_mov_b32_e32 v58, v57
	v_mov_b32_e32 v59, v57
	s_add_i32 s71, 0, 0x10000
	s_add_i32 s72, 0, 0x14000
	s_lshl_b32 s69, s6, 2
	v_lshlrev_b64 v[140:141], 9, v[132:133]
	v_add_u32_e32 v133, 0, v0
	s_add_i32 s75, s71, s41
	s_add_i32 s77, s72, s41
	s_add_i32 s69, s69, s3
	s_or_b32 s70, s33, 0xffffff00
	v_and_b32_e32 v138, 12, v177
	s_lshl_b32 s18, s65, 1
	s_add_i32 s73, s44, 0xc000
	s_add_i32 s74, s44, 0xe000
	s_add_i32 s76, s75, 0x2000
	s_add_i32 s78, s77, 0x2000
	s_add_i32 s79, 0, 0x18000
	s_mov_b32 s19, s4
	s_mov_b32 s6, s66
	s_mov_b32 s80, 0
	s_barrier
	s_branch .LBB0_639
.LBB0_638:
	s_and_b64 s[22:23], s[26:27], exec
	s_cselect_b32 s49, 8, 64
	s_lshl_b32 s3, s19, 3
	s_add_i32 s22, s70, s3
	s_lshr_b32 s6, s6, 9
	s_ashr_i32 s23, s22, 31
	s_lshl_b64 s[26:27], s[6:7], 22
	s_add_u32 s3, s58, s26
	s_addc_u32 s6, s59, s27
	s_lshl_b64 s[22:23], s[22:23], 17
	s_add_u32 s22, s3, s22
	s_addc_u32 s23, s6, s23
	v_lshl_add_u64 v[58:59], s[22:23], 0, v[140:141]
	s_mov_b32 s19, s7
	v_lshl_add_u64 v[58:59], v[58:59], 0, s[18:19]
	v_lshlrev_b32_e32 v56, 1, v138
	v_lshl_add_u64 v[58:59], v[58:59], 0, v[56:57]
	v_cvt_pk_bf16_f32 v112, v112, v113
	v_cvt_pk_bf16_f32 v113, v114, v115
	v_add_co_u32_e32 v114, vcc, s51, v58
	v_cvt_pk_bf16_f32 v96, v96, v97
	v_cvt_pk_bf16_f32 v97, v98, v99
	v_cvt_pk_bf16_f32 v80, v80, v81
	v_cvt_pk_bf16_f32 v81, v82, v83
	s_nop 1
	v_addc_co_u32_e32 v115, vcc, 0, v59, vcc
	v_add_co_u32_e32 v98, vcc, s62, v58
	v_cvt_pk_bf16_f32 v64, v64, v65
	v_cvt_pk_bf16_f32 v65, v66, v67
	v_cvt_pk_bf16_f32 v44, v44, v45
	v_cvt_pk_bf16_f32 v45, v46, v47
	s_nop 1
	v_addc_co_u32_e32 v99, vcc, 0, v59, vcc
	v_add_co_u32_e32 v82, vcc, s63, v58
	v_cvt_pk_bf16_f32 v28, v28, v29
	v_cvt_pk_bf16_f32 v29, v30, v31
	v_cvt_pk_bf16_f32 v12, v12, v13
	v_cvt_pk_bf16_f32 v13, v14, v15
	s_nop 1
	v_addc_co_u32_e32 v83, vcc, 0, v59, vcc
	v_add_co_u32_e32 v66, vcc, s48, v58
	v_cvt_pk_bf16_f32 v0, v0, v1
	v_cvt_pk_bf16_f32 v128, v128, v129
	v_cvt_pk_bf16_f32 v129, v130, v131
	v_cvt_pk_bf16_f32 v124, v124, v125
	s_nop 1
	v_addc_co_u32_e32 v67, vcc, 0, v59, vcc
	v_add_co_u32_e32 v46, vcc, s50, v58
	v_cvt_pk_bf16_f32 v125, v126, v127
	v_cvt_pk_bf16_f32 v120, v120, v121
	v_cvt_pk_bf16_f32 v121, v122, v123
	v_cvt_pk_bf16_f32 v116, v116, v117
	s_nop 1
	v_addc_co_u32_e32 v47, vcc, 0, v59, vcc
	v_add_co_u32_e32 v30, vcc, s60, v58
	v_cvt_pk_bf16_f32 v117, v118, v119
	v_cvt_pk_bf16_f32 v108, v108, v109
	v_cvt_pk_bf16_f32 v109, v110, v111
	v_cvt_pk_bf16_f32 v104, v104, v105
	s_nop 1
	v_addc_co_u32_e32 v31, vcc, 0, v59, vcc
	v_add_co_u32_e32 v14, vcc, s61, v58
	v_cvt_pk_bf16_f32 v105, v106, v107
	v_cvt_pk_bf16_f32 v100, v100, v101
	v_cvt_pk_bf16_f32 v101, v102, v103
	v_cvt_pk_bf16_f32 v92, v92, v93
	s_nop 1
	v_addc_co_u32_e32 v15, vcc, 0, v59, vcc
	v_cvt_pk_bf16_f32 v93, v94, v95
	v_cvt_pk_bf16_f32 v88, v88, v89
	v_cvt_pk_bf16_f32 v89, v90, v91
	v_cvt_pk_bf16_f32 v84, v84, v85
	v_cvt_pk_bf16_f32 v85, v86, v87
	v_cvt_pk_bf16_f32 v76, v76, v77
	v_cvt_pk_bf16_f32 v77, v78, v79
	v_cvt_pk_bf16_f32 v72, v72, v73
	v_cvt_pk_bf16_f32 v73, v74, v75
	v_cvt_pk_bf16_f32 v68, v68, v69
	v_cvt_pk_bf16_f32 v69, v70, v71
	v_cvt_pk_bf16_f32 v60, v60, v61
	v_cvt_pk_bf16_f32 v61, v62, v63
	v_cvt_pk_bf16_f32 v52, v52, v53
	v_cvt_pk_bf16_f32 v53, v54, v55
	v_cvt_pk_bf16_f32 v48, v48, v49
	v_cvt_pk_bf16_f32 v49, v50, v51
	v_cvt_pk_bf16_f32 v40, v40, v41
	v_cvt_pk_bf16_f32 v41, v42, v43
	v_cvt_pk_bf16_f32 v36, v36, v37
	v_cvt_pk_bf16_f32 v37, v38, v39
	v_cvt_pk_bf16_f32 v32, v32, v33
	v_cvt_pk_bf16_f32 v33, v34, v35
	v_cvt_pk_bf16_f32 v24, v24, v25
	v_cvt_pk_bf16_f32 v25, v26, v27
	v_cvt_pk_bf16_f32 v20, v20, v21
	v_cvt_pk_bf16_f32 v21, v22, v23
	v_cvt_pk_bf16_f32 v16, v16, v17
	v_cvt_pk_bf16_f32 v17, v18, v19
	v_cvt_pk_bf16_f32 v8, v8, v9
	v_cvt_pk_bf16_f32 v9, v10, v11
	v_cvt_pk_bf16_f32 v4, v4, v5
	v_cvt_pk_bf16_f32 v5, v6, v7
	v_cvt_pk_bf16_f32 v1, v2, v3
	global_store_dwordx2 v[14:15], v[0:1], off offset:288
	global_store_dwordx2 v[58:59], v[128:129], off
	global_store_dwordx2 v[58:59], v[124:125], off offset:32
	global_store_dwordx2 v[58:59], v[120:121], off offset:256
	global_store_dwordx2 v[58:59], v[116:117], off offset:288
	global_store_dwordx2 v[114:115], v[112:113], off
	global_store_dwordx2 v[114:115], v[108:109], off offset:32
	global_store_dwordx2 v[114:115], v[104:105], off offset:256
	global_store_dwordx2 v[114:115], v[100:101], off offset:288
	global_store_dwordx2 v[98:99], v[96:97], off
	global_store_dwordx2 v[98:99], v[92:93], off offset:32
	global_store_dwordx2 v[98:99], v[88:89], off offset:256
	global_store_dwordx2 v[98:99], v[84:85], off offset:288
	global_store_dwordx2 v[82:83], v[80:81], off
	global_store_dwordx2 v[82:83], v[76:77], off offset:32
	global_store_dwordx2 v[82:83], v[72:73], off offset:256
	global_store_dwordx2 v[82:83], v[68:69], off offset:288
	global_store_dwordx2 v[66:67], v[64:65], off
	global_store_dwordx2 v[66:67], v[60:61], off offset:32
	global_store_dwordx2 v[66:67], v[52:53], off offset:256
	global_store_dwordx2 v[66:67], v[48:49], off offset:288
	global_store_dwordx2 v[46:47], v[44:45], off
	global_store_dwordx2 v[46:47], v[40:41], off offset:32
	global_store_dwordx2 v[46:47], v[36:37], off offset:256
	global_store_dwordx2 v[46:47], v[32:33], off offset:288
	global_store_dwordx2 v[30:31], v[28:29], off
	global_store_dwordx2 v[30:31], v[24:25], off offset:32
	global_store_dwordx2 v[30:31], v[20:21], off offset:256
	global_store_dwordx2 v[30:31], v[16:17], off offset:288
	global_store_dwordx2 v[14:15], v[12:13], off
	global_store_dwordx2 v[14:15], v[8:9], off offset:32
	global_store_dwordx2 v[14:15], v[4:5], off offset:256
	s_mov_b32 s19, s10
	s_mov_b32 s6, s82
	s_mov_b64 s[22:23], s[24:25]
	s_mov_b32 s80, s81
	s_andn2_b64 vcc, exec, s[20:21]
	s_cbranch_vccz .LBB0_643
.LBB0_639:
	s_mov_b64 s[34:35], s[8:9]
	s_add_u32 s83, s34, 0x100
	s_addc_u32 s84, s35, 0
	v_add_co_u32_e64 v56, s[26:27], s80, 1
	s_and_b64 s[8:9], s[26:27], exec
	s_cselect_b32 s10, s4, s69
	s_cselect_b32 s82, s66, 0
	s_cmp_gt_i32 s80, 0
	s_cselect_b64 s[20:21], -1, 0
	s_ashr_i32 s11, s10, 31
	s_lshl_b64 s[8:9], s[10:11], 21
	s_add_u32 s3, s56, s8
	s_addc_u32 s8, s57, s9
	s_lshl_b32 s9, s82, 1
	s_add_u32 s24, s3, s9
	s_addc_u32 s25, s8, 0
	s_add_u32 s8, s42, s9
	s_addc_u32 s9, s43, 0
	s_cmp_lt_i32 s80, 1
	s_cselect_b64 s[28:29], -1, 0
	s_and_b64 s[36:37], s[28:29], exec
	s_cselect_b32 s11, s25, s23
	s_cselect_b32 s85, s24, s22
	s_cselect_b32 s86, s9, s35
	s_cselect_b32 s87, s8, s34
	s_lshl_b32 s3, s49, 7
	s_addk_i32 s3, 0xfc00
	v_readfirstlane_b32 s81, v56
	v_lshl_add_u64 v[58:59], s[22:23], 0, v[142:143]
	v_lshl_add_u64 v[146:147], s[22:23], 0, v[144:145]
	s_add_u32 s88, s3, 0x300
	s_mov_b64 s[34:35], 0
	s_mov_b32 s89, 0
	s_add_i32 s89, s89, 2
	v_add_u32_e32 v56, s71, v139
	s_add_u32 s3, s22, s34
	ds_read_b128 v[150:153], v56
	ds_read_b128 v[154:157], v56 offset:1024
	ds_read_b128 v[158:161], v56 offset:2048
	ds_read_b128 v[162:165], v56 offset:3072
	s_addc_u32 s36, s23, s35
	s_add_u32 s3, s3, 0x100
	s_addc_u32 s36, s36, 0
	s_add_u32 s90, s83, s34
	s_addc_u32 s37, s84, s35
	s_cmp_eq_u32 s88, s34
	s_cselect_b32 s39, s11, s36
	s_cselect_b32 s38, s85, s3
	s_cselect_b32 s37, s86, s37
	s_cselect_b32 s36, s87, s90
	s_mov_b32 m0, s73
	v_lshl_add_u64 v[174:175], v[58:59], 0, s[34:35]
	ds_read_b128 v[166:169], v133
	ds_read_b128 v[170:173], v133 offset:1024
	ds_read_b128 v[182:185], v133 offset:2048
	ds_read_b128 v[186:189], v133 offset:3072
	ds_read_b128 v[190:193], v133 offset:4096
	ds_read_b128 v[194:197], v133 offset:5120
	ds_read_b128 v[198:201], v133 offset:6144
	ds_read_b128 v[202:205], v133 offset:7168
	global_load_lds_dwordx4 v[174:175], off
	v_lshl_add_u64 v[174:175], v[146:147], 0, s[34:35]
	s_mov_b32 m0, s74
	s_nop 0
	global_load_lds_dwordx4 v[174:175], off
	s_waitcnt lgkmcnt(8)
	s_barrier
	s_waitcnt lgkmcnt(0)
	v_mfma_f32_16x16x32_bf16 v[128:131], v[150:153], v[166:169], 0
	v_mfma_f32_16x16x32_bf16 v[124:127], v[158:161], v[166:169], 0
	v_mfma_f32_16x16x32_bf16 v[112:115], v[150:153], v[182:185], 0
	v_mfma_f32_16x16x32_bf16 v[108:111], v[158:161], v[182:185], 0
	v_mfma_f32_16x16x32_bf16 v[96:99], v[150:153], v[190:193], 0
	v_mfma_f32_16x16x32_bf16 v[92:95], v[158:161], v[190:193], 0
	v_mfma_f32_16x16x32_bf16 v[80:83], v[150:153], v[198:201], 0
	v_mfma_f32_16x16x32_bf16 v[76:79], v[158:161], v[198:201], 0
	v_mfma_f32_16x16x32_bf16 v[128:131], v[154:157], v[170:173], v[128:131]
	v_mfma_f32_16x16x32_bf16 v[124:127], v[162:165], v[170:173], v[124:127]
	v_mfma_f32_16x16x32_bf16 v[112:115], v[154:157], v[186:189], v[112:115]
	v_mfma_f32_16x16x32_bf16 v[108:111], v[162:165], v[186:189], v[108:111]
	v_mfma_f32_16x16x32_bf16 v[96:99], v[154:157], v[194:197], v[96:99]
	v_mfma_f32_16x16x32_bf16 v[92:95], v[162:165], v[194:197], v[92:95]
	v_mfma_f32_16x16x32_bf16 v[80:83], v[154:157], v[202:205], v[80:83]
	v_mfma_f32_16x16x32_bf16 v[76:79], v[162:165], v[202:205], v[76:79]
	s_barrier
	s_mov_b32 m0, s75
	v_add_u32_e32 v56, s72, v139
	v_lshl_add_u64 v[174:175], s[36:37], 0, v[134:135]
	ds_read_b128 v[206:209], v56
	ds_read_b128 v[214:217], v56 offset:1024
	ds_read_b128 v[218:221], v56 offset:2048
	ds_read_b128 v[222:225], v56 offset:3072
	global_load_lds_dwordx4 v[174:175], off
	v_lshl_add_u64 v[226:227], s[36:37], 0, v[136:137]
	s_mov_b32 m0, s76
	s_nop 0
	global_load_lds_dwordx4 v[226:227], off
	s_barrier
	s_waitcnt lgkmcnt(0)
	v_mfma_f32_16x16x32_bf16 v[120:123], v[206:209], v[166:169], 0
	v_mfma_f32_16x16x32_bf16 v[116:119], v[218:221], v[166:169], 0
	v_mfma_f32_16x16x32_bf16 v[104:107], v[206:209], v[182:185], 0
	v_mfma_f32_16x16x32_bf16 v[100:103], v[218:221], v[182:185], 0
	v_mfma_f32_16x16x32_bf16 v[88:91], v[206:209], v[190:193], 0
	v_mfma_f32_16x16x32_bf16 v[84:87], v[218:221], v[190:193], 0
	v_mfma_f32_16x16x32_bf16 v[72:75], v[206:209], v[198:201], 0
	v_mfma_f32_16x16x32_bf16 v[68:71], v[218:221], v[198:201], 0
	v_mfma_f32_16x16x32_bf16 v[120:123], v[214:217], v[170:173], v[120:123]
	v_mfma_f32_16x16x32_bf16 v[116:119], v[222:225], v[170:173], v[116:119]
	v_mfma_f32_16x16x32_bf16 v[104:107], v[214:217], v[186:189], v[104:107]
	v_mfma_f32_16x16x32_bf16 v[100:103], v[222:225], v[186:189], v[100:103]
	v_mfma_f32_16x16x32_bf16 v[88:91], v[214:217], v[194:197], v[88:91]
	v_mfma_f32_16x16x32_bf16 v[84:87], v[222:225], v[194:197], v[84:87]
	v_mfma_f32_16x16x32_bf16 v[72:75], v[214:217], v[202:205], v[72:75]
	v_mfma_f32_16x16x32_bf16 v[68:71], v[222:225], v[202:205], v[68:71]
	s_mov_b32 m0, s44
	v_lshl_add_u64 v[228:229], s[38:39], 0, v[134:135]
	s_barrier
	ds_read_b128 v[166:169], v133 offset:16384
	ds_read_b128 v[170:173], v133 offset:17408
	ds_read_b128 v[182:185], v133 offset:18432
	ds_read_b128 v[186:189], v133 offset:19456
	ds_read_b128 v[190:193], v133 offset:20480
	ds_read_b128 v[194:197], v133 offset:21504
	ds_read_b128 v[198:201], v133 offset:22528
	ds_read_b128 v[202:205], v133 offset:23552
	global_load_lds_dwordx4 v[228:229], off
	v_lshl_add_u64 v[230:231], s[38:39], 0, v[136:137]
	s_mov_b32 m0, s45
	s_nop 0
	global_load_lds_dwordx4 v[230:231], off
	s_barrier
	s_waitcnt lgkmcnt(0)
	v_mfma_f32_16x16x32_bf16 v[64:67], v[150:153], v[166:169], 0
	v_mfma_f32_16x16x32_bf16 v[60:63], v[158:161], v[166:169], 0
	v_mfma_f32_16x16x32_bf16 v[44:47], v[150:153], v[182:185], 0
	v_mfma_f32_16x16x32_bf16 v[40:43], v[158:161], v[182:185], 0
	v_mfma_f32_16x16x32_bf16 v[28:31], v[150:153], v[190:193], 0
	v_mfma_f32_16x16x32_bf16 v[24:27], v[158:161], v[190:193], 0
	v_mfma_f32_16x16x32_bf16 v[12:15], v[150:153], v[198:201], 0
	v_mfma_f32_16x16x32_bf16 v[8:11], v[158:161], v[198:201], 0
	v_mfma_f32_16x16x32_bf16 v[64:67], v[154:157], v[170:173], v[64:67]
	v_mfma_f32_16x16x32_bf16 v[60:63], v[162:165], v[170:173], v[60:63]
	v_mfma_f32_16x16x32_bf16 v[44:47], v[154:157], v[186:189], v[44:47]
	v_mfma_f32_16x16x32_bf16 v[40:43], v[162:165], v[186:189], v[40:43]
	v_mfma_f32_16x16x32_bf16 v[28:31], v[154:157], v[194:197], v[28:31]
	v_mfma_f32_16x16x32_bf16 v[24:27], v[162:165], v[194:197], v[24:27]
	v_mfma_f32_16x16x32_bf16 v[12:15], v[154:157], v[202:205], v[12:15]
	v_mfma_f32_16x16x32_bf16 v[8:11], v[162:165], v[202:205], v[8:11]
	s_barrier
	s_add_u32 s90, s36, 0x100000
	s_addc_u32 s91, s37, 0
	s_mov_b32 m0, s77
	v_lshl_add_u64 v[150:151], s[90:91], 0, v[134:135]
	global_load_lds_dwordx4 v[150:151], off
	v_lshl_add_u64 v[150:151], s[90:91], 0, v[136:137]
	s_mov_b32 m0, s78
	s_nop 0
	global_load_lds_dwordx4 v[150:151], off
	s_waitcnt vmcnt(6)
	s_barrier
	v_mfma_f32_16x16x32_bf16 v[52:55], v[206:209], v[166:169], 0
	v_mfma_f32_16x16x32_bf16 v[48:51], v[218:221], v[166:169], 0
	v_mfma_f32_16x16x32_bf16 v[36:39], v[206:209], v[182:185], 0
	v_mfma_f32_16x16x32_bf16 v[32:35], v[218:221], v[182:185], 0
	v_mfma_f32_16x16x32_bf16 v[20:23], v[206:209], v[190:193], 0
	v_mfma_f32_16x16x32_bf16 v[16:19], v[218:221], v[190:193], 0
	v_mfma_f32_16x16x32_bf16 v[4:7], v[206:209], v[198:201], 0
	v_mfma_f32_16x16x32_bf16 v[0:3], v[218:221], v[198:201], 0
	v_mfma_f32_16x16x32_bf16 v[52:55], v[214:217], v[170:173], v[52:55]
	v_mfma_f32_16x16x32_bf16 v[48:51], v[222:225], v[170:173], v[48:51]
	v_mfma_f32_16x16x32_bf16 v[36:39], v[214:217], v[186:189], v[36:39]
	v_mfma_f32_16x16x32_bf16 v[32:35], v[222:225], v[186:189], v[32:35]
	v_mfma_f32_16x16x32_bf16 v[20:23], v[214:217], v[194:197], v[20:23]
	v_mfma_f32_16x16x32_bf16 v[16:19], v[222:225], v[194:197], v[16:19]
	v_mfma_f32_16x16x32_bf16 v[4:7], v[214:217], v[202:205], v[4:7]
	v_mfma_f32_16x16x32_bf16 v[0:3], v[222:225], v[202:205], v[0:3]
	v_add_u32_e32 v56, s79, v139
	s_barrier
	ds_read_b128 v[150:153], v56
	ds_read_b128 v[154:157], v56 offset:1024
	ds_read_b128 v[158:161], v56 offset:2048
	ds_read_b128 v[162:165], v56 offset:3072
	s_add_u32 s38, s38, 0x100000
	s_addc_u32 s39, s39, 0
	s_mov_b32 m0, s46
	v_lshl_add_u64 v[206:207], s[38:39], 0, v[134:135]
	ds_read_b128 v[166:169], v133 offset:32768
	ds_read_b128 v[170:173], v133 offset:33792
	ds_read_b128 v[182:185], v133 offset:34816
	ds_read_b128 v[186:189], v133 offset:35840
	ds_read_b128 v[190:193], v133 offset:36864
	ds_read_b128 v[194:197], v133 offset:37888
	ds_read_b128 v[198:201], v133 offset:38912
	ds_read_b128 v[202:205], v133 offset:39936
	global_load_lds_dwordx4 v[206:207], off
	v_lshl_add_u64 v[206:207], s[38:39], 0, v[136:137]
	s_mov_b32 m0, s47
	s_nop 0
	global_load_lds_dwordx4 v[206:207], off
	s_waitcnt lgkmcnt(8)
	s_barrier
	s_waitcnt lgkmcnt(0)
	v_mfma_f32_16x16x32_bf16 v[128:131], v[150:153], v[166:169], v[128:131]
	v_mfma_f32_16x16x32_bf16 v[124:127], v[158:161], v[166:169], v[124:127]
	v_mfma_f32_16x16x32_bf16 v[112:115], v[150:153], v[182:185], v[112:115]
	v_mfma_f32_16x16x32_bf16 v[108:111], v[158:161], v[182:185], v[108:111]
	v_mfma_f32_16x16x32_bf16 v[96:99], v[150:153], v[190:193], v[96:99]
	v_mfma_f32_16x16x32_bf16 v[92:95], v[158:161], v[190:193], v[92:95]
	v_mfma_f32_16x16x32_bf16 v[80:83], v[150:153], v[198:201], v[80:83]
	v_mfma_f32_16x16x32_bf16 v[76:79], v[158:161], v[198:201], v[76:79]
	v_mfma_f32_16x16x32_bf16 v[128:131], v[154:157], v[170:173], v[128:131]
	v_mfma_f32_16x16x32_bf16 v[124:127], v[162:165], v[170:173], v[124:127]
	v_mfma_f32_16x16x32_bf16 v[112:115], v[154:157], v[186:189], v[112:115]
	v_mfma_f32_16x16x32_bf16 v[108:111], v[162:165], v[186:189], v[108:111]
	v_mfma_f32_16x16x32_bf16 v[96:99], v[154:157], v[194:197], v[96:99]
	v_mfma_f32_16x16x32_bf16 v[92:95], v[162:165], v[194:197], v[92:95]
	v_mfma_f32_16x16x32_bf16 v[80:83], v[154:157], v[202:205], v[80:83]
	v_mfma_f32_16x16x32_bf16 v[76:79], v[162:165], v[202:205], v[76:79]
	s_barrier
	s_add_i32 s3, 0, 0x1c000
	s_add_i32 s38, s79, s41
	v_add_u32_e32 v56, s3, v139
	v_lshl_add_u64 v[174:175], v[174:175], 0, s[16:17]
	s_mov_b32 m0, s38
	ds_read_b128 v[206:209], v56
	ds_read_b128 v[214:217], v56 offset:1024
	ds_read_b128 v[218:221], v56 offset:2048
	ds_read_b128 v[222:225], v56 offset:3072
	global_load_lds_dwordx4 v[174:175], off
	v_lshl_add_u64 v[174:175], v[226:227], 0, s[16:17]
	s_add_i32 m0, s38, 0x2000
	s_nop 0
	global_load_lds_dwordx4 v[174:175], off
	s_barrier
	s_waitcnt lgkmcnt(0)
	v_mfma_f32_16x16x32_bf16 v[120:123], v[206:209], v[166:169], v[120:123]
	v_mfma_f32_16x16x32_bf16 v[116:119], v[218:221], v[166:169], v[116:119]
	v_mfma_f32_16x16x32_bf16 v[104:107], v[206:209], v[182:185], v[104:107]
	v_mfma_f32_16x16x32_bf16 v[100:103], v[218:221], v[182:185], v[100:103]
	v_mfma_f32_16x16x32_bf16 v[88:91], v[206:209], v[190:193], v[88:91]
	v_mfma_f32_16x16x32_bf16 v[84:87], v[218:221], v[190:193], v[84:87]
	v_mfma_f32_16x16x32_bf16 v[72:75], v[206:209], v[198:201], v[72:75]
	v_mfma_f32_16x16x32_bf16 v[68:71], v[218:221], v[198:201], v[68:71]
	v_mfma_f32_16x16x32_bf16 v[120:123], v[214:217], v[170:173], v[120:123]
	v_mfma_f32_16x16x32_bf16 v[116:119], v[222:225], v[170:173], v[116:119]
	v_mfma_f32_16x16x32_bf16 v[104:107], v[214:217], v[186:189], v[104:107]
	v_mfma_f32_16x16x32_bf16 v[100:103], v[222:225], v[186:189], v[100:103]
	v_mfma_f32_16x16x32_bf16 v[88:91], v[214:217], v[194:197], v[88:91]
	v_mfma_f32_16x16x32_bf16 v[84:87], v[222:225], v[194:197], v[84:87]
	v_mfma_f32_16x16x32_bf16 v[72:75], v[214:217], v[202:205], v[72:75]
	v_mfma_f32_16x16x32_bf16 v[68:71], v[222:225], v[202:205], v[68:71]
	s_mov_b32 m0, s67
	v_lshl_add_u64 v[174:175], v[228:229], 0, s[16:17]
	s_barrier
	ds_read_b128 v[166:169], v133 offset:49152
	ds_read_b128 v[170:173], v133 offset:50176
	ds_read_b128 v[182:185], v133 offset:51200
	ds_read_b128 v[186:189], v133 offset:52224
	ds_read_b128 v[190:193], v133 offset:53248
	ds_read_b128 v[194:197], v133 offset:54272
	ds_read_b128 v[198:201], v133 offset:55296
	ds_read_b128 v[202:205], v133 offset:56320
	global_load_lds_dwordx4 v[174:175], off
	v_lshl_add_u64 v[174:175], v[230:231], 0, s[16:17]
	s_mov_b32 m0, s68
	s_nop 0
	global_load_lds_dwordx4 v[174:175], off
	s_barrier
	s_waitcnt lgkmcnt(0)
	v_mfma_f32_16x16x32_bf16 v[64:67], v[150:153], v[166:169], v[64:67]
	v_mfma_f32_16x16x32_bf16 v[60:63], v[158:161], v[166:169], v[60:63]
	v_mfma_f32_16x16x32_bf16 v[44:47], v[150:153], v[182:185], v[44:47]
	v_mfma_f32_16x16x32_bf16 v[40:43], v[158:161], v[182:185], v[40:43]
	v_mfma_f32_16x16x32_bf16 v[28:31], v[150:153], v[190:193], v[28:31]
	v_mfma_f32_16x16x32_bf16 v[24:27], v[158:161], v[190:193], v[24:27]
	v_mfma_f32_16x16x32_bf16 v[12:15], v[150:153], v[198:201], v[12:15]
	v_mfma_f32_16x16x32_bf16 v[8:11], v[158:161], v[198:201], v[8:11]
	v_mfma_f32_16x16x32_bf16 v[64:67], v[154:157], v[170:173], v[64:67]
	v_mfma_f32_16x16x32_bf16 v[60:63], v[162:165], v[170:173], v[60:63]
	v_mfma_f32_16x16x32_bf16 v[44:47], v[154:157], v[186:189], v[44:47]
	v_mfma_f32_16x16x32_bf16 v[40:43], v[162:165], v[186:189], v[40:43]
	v_mfma_f32_16x16x32_bf16 v[28:31], v[154:157], v[194:197], v[28:31]
	v_mfma_f32_16x16x32_bf16 v[24:27], v[162:165], v[194:197], v[24:27]
	v_mfma_f32_16x16x32_bf16 v[12:15], v[154:157], v[202:205], v[12:15]
	v_mfma_f32_16x16x32_bf16 v[8:11], v[162:165], v[202:205], v[8:11]
	s_barrier
	s_add_u32 s36, s36, 0x100080
	s_addc_u32 s37, s37, 0
	s_add_i32 s3, s3, s41
	v_lshl_add_u64 v[150:151], s[36:37], 0, v[134:135]
	s_mov_b32 m0, s3
	s_nop 0
	global_load_lds_dwordx4 v[150:151], off
	v_lshl_add_u64 v[150:151], s[36:37], 0, v[136:137]
	s_add_i32 m0, s3, 0x2000
	s_nop 0
	global_load_lds_dwordx4 v[150:151], off
	s_waitcnt vmcnt(6)
	s_barrier
	v_mfma_f32_16x16x32_bf16 v[52:55], v[206:209], v[166:169], v[52:55]
	v_mfma_f32_16x16x32_bf16 v[48:51], v[218:221], v[166:169], v[48:51]
	v_mfma_f32_16x16x32_bf16 v[36:39], v[206:209], v[182:185], v[36:39]
	v_mfma_f32_16x16x32_bf16 v[32:35], v[218:221], v[182:185], v[32:35]
	v_mfma_f32_16x16x32_bf16 v[20:23], v[206:209], v[190:193], v[20:23]
	v_mfma_f32_16x16x32_bf16 v[16:19], v[218:221], v[190:193], v[16:19]
	v_mfma_f32_16x16x32_bf16 v[4:7], v[206:209], v[198:201], v[4:7]
	v_mfma_f32_16x16x32_bf16 v[0:3], v[218:221], v[198:201], v[0:3]
	v_mfma_f32_16x16x32_bf16 v[52:55], v[214:217], v[170:173], v[52:55]
	v_mfma_f32_16x16x32_bf16 v[48:51], v[222:225], v[170:173], v[48:51]
	v_mfma_f32_16x16x32_bf16 v[36:39], v[214:217], v[186:189], v[36:39]
	v_mfma_f32_16x16x32_bf16 v[32:35], v[222:225], v[186:189], v[32:35]
	v_mfma_f32_16x16x32_bf16 v[20:23], v[214:217], v[194:197], v[20:23]
	v_mfma_f32_16x16x32_bf16 v[16:19], v[222:225], v[194:197], v[16:19]
	v_mfma_f32_16x16x32_bf16 v[4:7], v[214:217], v[202:205], v[4:7]
	v_mfma_f32_16x16x32_bf16 v[0:3], v[222:225], v[202:205], v[0:3]
	s_add_u32 s34, s34, 0x100
	s_addc_u32 s35, s35, 0
	s_cmp_ge_u32 s89, s49
	s_barrier
	s_cbranch_scc1 .Lpeel_done_out

.Lpeel_done_out:
	s_add_u32 s34, s83, 0xffffff00
	s_addc_u32 s35, s84, -1
	s_and_b64 vcc, exec, s[28:29]
	s_cbranch_vccnz .LBB0_638
	s_mov_b64 s[8:9], s[34:35]
	s_andn2_b64 vcc, exec, s[20:21]
	s_cbranch_vccnz .LBB0_639
